# gmlp: hoist chunk-invariant spatial weights and biases out of the chunk loop (on top of peel)
# speedup vs baseline: 1.0173x; 1.0061x over previous
.LBB0_237:
	v_mov_b32_e32 v32, v242
	s_waitcnt vmcnt(63) expcnt(7) lgkmcnt(15)
	s_barrier
	s_load_dword s3, s[54:55], 0x0
	s_mov_b32 s9, s76
	s_waitcnt lgkmcnt(0)
	s_cmpk_gt_i32 s9, 0x1ff
	v_readfirstlane_b32 s11, v32
	s_cbranch_scc1 .LBB0_242
	s_lshl_b32 s0, s56, 9
	s_lshl_b64 s[18:19], s[0:1], 2
	s_add_u32 s18, s42, s18
	s_addc_u32 s19, s43, s19
	s_add_u32 s22, s84, s2
	v_and_b32_e32 v37, 0x7f, v32
	s_addc_u32 s23, s85, 0
	s_lshl_b32 s20, s9, 7
	v_ashrrev_i32_e32 v33, 7, v32
	v_or_b32_e32 v2, s20, v37
	v_mov_b64_e32 v[0:1], s[50:51]
	v_mad_i64_i32 v[0:1], s[24:25], v2, s6, v[0:1]
	v_lshlrev_b32_e32 v2, 6, v33
	v_ashrrev_i32_e32 v3, 31, v2
	v_lshlrev_b64 v[34:35], 1, v[2:3]
	v_lshl_add_u64 v[28:29], v[0:1], 0, v[34:35]
	global_load_dwordx4 v[0:3], v[28:29], off offset:3120
	global_load_dwordx4 v[4:7], v[28:29], off offset:3104
	global_load_dwordx4 v[8:11], v[28:29], off offset:3088
	global_load_dwordx4 v[12:15], v[28:29], off offset:3072
	global_load_dwordx4 v[16:19], v[28:29], off offset:3184
	global_load_dwordx4 v[20:23], v[28:29], off offset:3168
	global_load_dwordx4 v[24:27], v[28:29], off offset:3152
	s_nop 0
	global_load_dwordx4 v[28:31], v[28:29], off offset:3136
	s_ashr_i32 s0, s11, 2
	v_bfe_u32 v39, v32, 4, 2
	v_bfi_b32 v38, -16, s0, v32
	s_and_b32 s2, s0, -16
	v_lshlrev_b32_e32 v36, 2, v39
	v_lshlrev_b32_e32 v208, 3, v39
	v_lshlrev_b32_e32 v40, 4, v39
	v_mov_b32_e32 v41, v209
	s_movk_i32 s0, 0x4400
	v_ashrrev_i32_e32 v39, 31, v38
	v_and_b32_e32 v42, 15, v32
	v_lshl_add_u64 v[40:41], s[22:23], 0, v[40:41]
	v_mul_lo_u32 v44, v33, s0
	v_and_b32_e32 v45, 48, v32
	v_lshlrev_b64 v[32:33], 8, v[38:39]
	v_lshl_add_u64 v[98:99], v[38:39], 2, s[18:19]
	v_lshl_add_u64 v[32:33], v[40:41], 0, v[32:33]
	s_mov_b64 s[18:19], 0x130000
	v_lshl_add_u64 v[100:101], v[32:33], 0, s[18:19]
	s_mov_b64 s[18:19], 0x138000
	v_lshl_add_u64 v[102:103], v[32:33], 0, s[18:19]
	s_mov_b64 s[18:19], 0x140000
	v_lshlrev_b32_e32 v43, 1, v37
	s_ashr_i32 s11, s2, 31
	v_mul_u32_u24_e32 v38, 0x110, v42
	v_lshl_add_u64 v[104:105], v[32:33], 0, s[18:19]
	s_mov_b64 s[18:19], 0x148000
	s_lshl_b32 s0, s3, 7
	v_or_b32_e32 v96, s2, v42
	v_mov_b32_e32 v97, s11
	v_lshl_add_u64 v[106:107], v[32:33], 0, s[18:19]
	v_add3_u32 v123, 0, v44, v43
	v_add3_u32 v133, 0, v45, v38
	v_lshl_add_u64 v[108:109], s[50:51], 0, v[208:209]
	v_lshl_add_u64 v[110:111], s[50:51], 0, v[34:35]
	v_or_b32_e32 v143, s0, v37
	s_add_i32 s2, s9, s3
	v_lshlrev_b32_e32 v208, 1, v36
	global_load_dword v234, v[98:99], off
	global_load_dword v236, v[98:99], off offset:512
	global_load_dword v238, v[98:99], off offset:1024
	global_load_dword v240, v[98:99], off offset:1536
	global_load_dwordx4 v[164:167], v[100:101], off
	global_load_dwordx4 v[168:171], v[104:105], off offset:192
	global_load_dwordx4 v[172:175], v[100:101], off offset:64
	global_load_dwordx4 v[176:179], v[100:101], off offset:128
	global_load_dwordx4 v[180:183], v[100:101], off offset:192
	global_load_dwordx4 v[184:187], v[102:103], off
	global_load_dwordx4 v[188:191], v[102:103], off offset:64
	global_load_dwordx4 v[192:195], v[102:103], off offset:128
	global_load_dwordx4 v[196:199], v[102:103], off offset:192
	global_load_dwordx4 v[200:203], v[104:105], off
	global_load_dwordx4 v[204:207], v[104:105], off offset:64
	global_load_dwordx4 v[214:217], v[104:105], off offset:128
	global_load_dwordx4 v[218:221], v[106:107], off
	global_load_dwordx4 v[222:225], v[106:107], off offset:64
	global_load_dwordx4 v[226:229], v[106:107], off offset:128
	global_load_dwordx4 v[230:233], v[106:107], off offset:192
	s_waitcnt vmcnt(0)
	s_branch .LBB0_240
.LBB0_239:
	v_lshlrev_b64 v[32:33], 11, v[32:33]
	v_lshl_add_u64 v[112:113], s[84:85], 0, v[32:33]
	ds_read_b128 v[36:39], v133
	ds_read_b128 v[80:83], v133 offset:47872
	ds_read_b128 v[40:43], v133 offset:4352
	ds_read_b128 v[52:55], v133 offset:64
	ds_read_b128 v[44:47], v133 offset:8704
	ds_read_b128 v[48:51], v133 offset:13056
	ds_read_b128 v[72:75], v133 offset:39168
	ds_read_b128 v[76:79], v133 offset:43520
	s_mov_b64 s[18:19], 0x1a000600
	s_add_i32 s9, s9, s3
	s_add_i32 s20, s20, s0
	s_add_i32 s2, s2, s3
	s_cmpk_lt_i32 s9, 0x200
	s_waitcnt lgkmcnt(7)
	v_mfma_f32_16x16x32_bf16 v[36:39], v[36:39], v[164:167], 0
	ds_read_b128 v[60:63], v133 offset:26112
	ds_read_b128 v[68:71], v133 offset:17472
	s_waitcnt lgkmcnt(7)
	v_mfma_f32_16x16x32_bf16 v[40:43], v[40:43], v[164:167], 0
	ds_read_b128 v[64:67], v133 offset:30464
	ds_read_b128 v[56:59], v133 offset:21760
	ds_read_b128 v[84:87], v133 offset:34880
	s_waitcnt lgkmcnt(8)
	v_mfma_f32_16x16x32_bf16 v[44:47], v[44:47], v[164:167], 0
	ds_read_b128 v[154:157], v133 offset:65280
	ds_read_b128 v[158:161], v133 offset:52288
	ds_read_b128 v[92:95], v133 offset:60928
	s_waitcnt lgkmcnt(10)
	v_mfma_f32_16x16x32_bf16 v[32:35], v[48:51], v[164:167], 0
	v_mfma_f32_16x16x32_bf16 v[36:39], v[52:55], v[172:175], v[36:39]
	ds_read_b128 v[52:55], v133 offset:4416
	s_waitcnt lgkmcnt(0)
	v_mfma_f32_16x16x32_bf16 v[40:43], v[52:55], v[172:175], v[40:43]
	ds_read_b128 v[52:55], v133 offset:8768
	s_waitcnt lgkmcnt(0)
	v_mfma_f32_16x16x32_bf16 v[44:47], v[52:55], v[172:175], v[44:47]
	ds_read_b128 v[52:55], v133 offset:13120
	s_waitcnt lgkmcnt(0)
	v_mfma_f32_16x16x32_bf16 v[32:35], v[52:55], v[172:175], v[32:35]
	ds_read_b128 v[52:55], v133 offset:128
	s_waitcnt lgkmcnt(0)
	v_mfma_f32_16x16x32_bf16 v[36:39], v[52:55], v[176:179], v[36:39]
	ds_read_b128 v[52:55], v133 offset:4480
	s_waitcnt lgkmcnt(0)
	v_mfma_f32_16x16x32_bf16 v[40:43], v[52:55], v[176:179], v[40:43]
	ds_read_b128 v[52:55], v133 offset:8832
	s_waitcnt lgkmcnt(0)
	v_mfma_f32_16x16x32_bf16 v[52:55], v[52:55], v[176:179], v[44:47]
	s_nop 2
	ds_read_b128 v[44:47], v133 offset:13184
	s_waitcnt lgkmcnt(0)
	v_mfma_f32_16x16x32_bf16 v[32:35], v[44:47], v[176:179], v[32:35]
	ds_read_b128 v[44:47], v133 offset:192
	s_waitcnt lgkmcnt(0)
	v_mfma_f32_16x16x32_bf16 v[44:47], v[44:47], v[180:183], v[36:39]
	s_nop 2
	ds_read_b128 v[36:39], v133 offset:4544
	s_nop 3
	v_pk_add_f32 v[44:45], v[234:235], v[44:45] op_sel_hi:[0,1]
	s_waitcnt lgkmcnt(0)
	v_mfma_f32_16x16x32_bf16 v[40:43], v[36:39], v[180:183], v[40:43]
	ds_read_b128 v[36:39], v133 offset:8896
	v_pk_add_f32 v[46:47], v[234:235], v[46:47] op_sel_hi:[0,1]
	s_nop 5
	v_pk_add_f32 v[42:43], v[234:235], v[42:43] op_sel_hi:[0,1]
	s_waitcnt lgkmcnt(0)
	v_mfma_f32_16x16x32_bf16 v[36:39], v[36:39], v[180:183], v[52:55]
	s_nop 2
	ds_read_b128 v[52:55], v133 offset:13248
	v_pk_add_f32 v[40:41], v[234:235], v[40:41] op_sel_hi:[0,1]
	s_nop 2
	v_add_f32_e32 v37, v234, v37
	s_waitcnt lgkmcnt(0)
	v_mfma_f32_16x16x32_bf16 v[32:35], v[52:55], v[180:183], v[32:35]
	ds_read_b128 v[52:55], v133 offset:17408
	v_add_f32_e32 v38, v234, v38
	s_waitcnt lgkmcnt(0)
	v_mfma_f32_16x16x32_bf16 v[52:55], v[52:55], v[184:187], 0
	v_add_f32_e32 v36, v234, v36
	v_add_f32_e32 v39, v234, v39
	s_nop 0
	v_add_f32_e32 v32, v234, v32
	v_mfma_f32_16x16x32_bf16 v[56:59], v[56:59], v[184:187], 0
	v_add_f32_e32 v33, v234, v33
	v_mfma_f32_16x16x32_bf16 v[60:63], v[60:63], v[184:187], 0
	v_mfma_f32_16x16x32_bf16 v[48:51], v[64:67], v[184:187], 0
	v_mfma_f32_16x16x32_bf16 v[52:55], v[68:71], v[188:191], v[52:55]
	ds_read_b128 v[68:71], v133 offset:21824
	s_waitcnt lgkmcnt(0)
	v_mfma_f32_16x16x32_bf16 v[56:59], v[68:71], v[188:191], v[56:59]
	ds_read_b128 v[68:71], v133 offset:26176
	s_waitcnt lgkmcnt(0)
	v_mfma_f32_16x16x32_bf16 v[60:63], v[68:71], v[188:191], v[60:63]
	ds_read_b128 v[68:71], v133 offset:30528
	s_waitcnt lgkmcnt(0)
	v_mfma_f32_16x16x32_bf16 v[48:51], v[68:71], v[188:191], v[48:51]
	ds_read_b128 v[68:71], v133 offset:17536
	s_waitcnt lgkmcnt(0)
	v_mfma_f32_16x16x32_bf16 v[52:55], v[68:71], v[192:195], v[52:55]
	ds_read_b128 v[68:71], v133 offset:21888
	s_waitcnt lgkmcnt(0)
	v_mfma_f32_16x16x32_bf16 v[56:59], v[68:71], v[192:195], v[56:59]
	ds_read_b128 v[68:71], v133 offset:26240
	s_waitcnt lgkmcnt(0)
	v_mfma_f32_16x16x32_bf16 v[68:71], v[68:71], v[192:195], v[60:63]
	s_nop 2
	ds_read_b128 v[60:63], v133 offset:30592
	s_waitcnt lgkmcnt(0)
	v_mfma_f32_16x16x32_bf16 v[48:51], v[60:63], v[192:195], v[48:51]
	ds_read_b128 v[60:63], v133 offset:17600
	s_waitcnt lgkmcnt(0)
	v_mfma_f32_16x16x32_bf16 v[60:63], v[60:63], v[196:199], v[52:55]
	s_nop 2
	ds_read_b128 v[52:55], v133 offset:21952
	s_waitcnt lgkmcnt(0)
	v_mfma_f32_16x16x32_bf16 v[56:59], v[52:55], v[196:199], v[56:59]
	ds_read_b128 v[52:55], v133 offset:26304
	s_nop 6
	v_pk_add_f32 v[56:57], v[236:237], v[56:57] op_sel_hi:[0,1]
	s_waitcnt lgkmcnt(0)
	v_mfma_f32_16x16x32_bf16 v[52:55], v[52:55], v[196:199], v[68:71]
	s_nop 2
	ds_read_b128 v[68:71], v133 offset:30656
	v_pk_add_f32 v[58:59], v[236:237], v[58:59] op_sel_hi:[0,1]
	s_waitcnt lgkmcnt(0)
	v_mfma_f32_16x16x32_bf16 v[48:51], v[68:71], v[196:199], v[48:51]
	ds_read_b128 v[68:71], v133 offset:34816
	s_waitcnt lgkmcnt(0)
	v_mfma_f32_16x16x32_bf16 v[68:71], v[68:71], v[200:203], 0
	v_mfma_f32_16x16x32_bf16 v[72:75], v[72:75], v[200:203], 0
	v_mfma_f32_16x16x32_bf16 v[76:79], v[76:79], v[200:203], 0
	v_mfma_f32_16x16x32_bf16 v[64:67], v[80:83], v[200:203], 0
	v_mfma_f32_16x16x32_bf16 v[68:71], v[84:87], v[204:207], v[68:71]
	ds_read_b128 v[84:87], v133 offset:39232
	s_waitcnt lgkmcnt(0)
	v_mfma_f32_16x16x32_bf16 v[72:75], v[84:87], v[204:207], v[72:75]
	ds_read_b128 v[84:87], v133 offset:43584
	s_waitcnt lgkmcnt(0)
	v_mfma_f32_16x16x32_bf16 v[76:79], v[84:87], v[204:207], v[76:79]
	ds_read_b128 v[84:87], v133 offset:47936
	s_waitcnt lgkmcnt(0)
	v_mfma_f32_16x16x32_bf16 v[64:67], v[84:87], v[204:207], v[64:67]
	ds_read_b128 v[84:87], v133 offset:34944
	s_waitcnt lgkmcnt(0)
	v_mfma_f32_16x16x32_bf16 v[68:71], v[84:87], v[214:217], v[68:71]
	ds_read_b128 v[84:87], v133 offset:39296
	s_waitcnt lgkmcnt(0)
	v_mfma_f32_16x16x32_bf16 v[72:75], v[84:87], v[214:217], v[72:75]
	ds_read_b128 v[84:87], v133 offset:43648
	s_waitcnt lgkmcnt(0)
	v_mfma_f32_16x16x32_bf16 v[84:87], v[84:87], v[214:217], v[76:79]
	s_nop 2
	ds_read_b128 v[76:79], v133 offset:48000
	s_waitcnt lgkmcnt(0)
	v_mfma_f32_16x16x32_bf16 v[80:83], v[76:79], v[214:217], v[64:67]
	s_nop 2
	ds_read_b128 v[64:67], v133 offset:35008
	s_waitcnt lgkmcnt(0)
	v_mfma_f32_16x16x32_bf16 v[76:79], v[64:67], v[168:171], v[68:71]
	ds_read_b128 v[64:67], v133 offset:39360
	s_nop 1
	ds_read_b128 v[68:71], v133 offset:48064
	s_waitcnt lgkmcnt(0)
	v_mfma_f32_16x16x32_bf16 v[68:71], v[68:71], v[168:171], v[80:83]
	s_nop 2
	v_mfma_f32_16x16x32_bf16 v[72:75], v[64:67], v[168:171], v[72:75]
	ds_read_b128 v[64:67], v133 offset:43712
	s_waitcnt lgkmcnt(0)
	v_mfma_f32_16x16x32_bf16 v[64:67], v[64:67], v[168:171], v[84:87]
	s_nop 2
	ds_read_b128 v[84:87], v133 offset:52224
	ds_read_b128 v[88:91], v133 offset:56576
	v_pk_add_f32 v[72:73], v[238:239], v[72:73] op_sel_hi:[0,1]
	s_waitcnt lgkmcnt(1)
	v_mfma_f32_16x16x32_bf16 v[84:87], v[84:87], v[218:221], 0
	v_add_f32_e64 v74, v238, v74
	v_add_f32_e64 v75, v238, v75
	s_waitcnt lgkmcnt(0)
	v_mfma_f32_16x16x32_bf16 v[88:91], v[88:91], v[218:221], 0
	v_mfma_f32_16x16x32_bf16 v[92:95], v[92:95], v[218:221], 0
	v_mfma_f32_16x16x32_bf16 v[80:83], v[154:157], v[218:221], 0
	v_mfma_f32_16x16x32_bf16 v[84:87], v[158:161], v[222:225], v[84:87]
	ds_read_b128 v[158:161], v133 offset:56640
	s_waitcnt lgkmcnt(0)
	v_mfma_f32_16x16x32_bf16 v[88:91], v[158:161], v[222:225], v[88:91]
	ds_read_b128 v[158:161], v133 offset:60992
	s_waitcnt lgkmcnt(0)
	v_mfma_f32_16x16x32_bf16 v[92:95], v[158:161], v[222:225], v[92:95]
	ds_read_b128 v[158:161], v133 offset:65344
	s_waitcnt lgkmcnt(0)
	v_mfma_f32_16x16x32_bf16 v[80:83], v[158:161], v[222:225], v[80:83]
	ds_read_b128 v[158:161], v133 offset:52352
	s_waitcnt lgkmcnt(0)
	v_mfma_f32_16x16x32_bf16 v[84:87], v[158:161], v[226:229], v[84:87]
	ds_read_b128 v[158:161], v133 offset:56704
	s_waitcnt lgkmcnt(0)
	v_mfma_f32_16x16x32_bf16 v[88:91], v[158:161], v[226:229], v[88:91]
	ds_read_b128 v[158:161], v133 offset:61056
	s_waitcnt lgkmcnt(0)
	v_mfma_f32_16x16x32_bf16 v[158:161], v[158:161], v[226:229], v[92:95]
	s_nop 2
	ds_read_b128 v[92:95], v133 offset:65408
	s_waitcnt lgkmcnt(0)
	v_mfma_f32_16x16x32_bf16 v[80:83], v[92:95], v[226:229], v[80:83]
	ds_read_b128 v[92:95], v133 offset:52416
	s_waitcnt lgkmcnt(0)
	v_mfma_f32_16x16x32_bf16 v[92:95], v[92:95], v[230:233], v[84:87]
	s_nop 2
	ds_read_b128 v[84:87], v133 offset:56768
	s_waitcnt lgkmcnt(0)
	v_mfma_f32_16x16x32_bf16 v[88:91], v[84:87], v[230:233], v[88:91]
	ds_read_b128 v[84:87], v133 offset:61120
	s_nop 6
	v_pk_add_f32 v[90:91], v[240:241], v[90:91] op_sel_hi:[0,1]
	s_waitcnt lgkmcnt(0)
	v_mfma_f32_16x16x32_bf16 v[84:87], v[84:87], v[230:233], v[158:161]
	s_nop 2
	ds_read_b128 v[158:161], v133 offset:65472
	v_pk_add_f32 v[88:89], v[240:241], v[88:89] op_sel_hi:[0,1]
	s_waitcnt lgkmcnt(0)
	v_mfma_f32_16x16x32_bf16 v[80:83], v[158:161], v[230:233], v[80:83]
	s_waitcnt vmcnt(0)
	v_lshlrev_b32_e32 v154, 16, v152
	v_and_b32_e32 v155, 0xffff0000, v152
	v_pk_mul_f32 v[44:45], v[44:45], v[154:155]
	v_lshlrev_b32_e32 v154, 16, v148
	v_and_b32_e32 v155, 0xffff0000, v148
	v_lshlrev_b32_e32 v148, 16, v149
	v_and_b32_e32 v149, 0xffff0000, v149
	v_pk_mul_f32 v[42:43], v[42:43], v[148:149]
	v_pk_mul_f32 v[40:41], v[40:41], v[154:155]
	v_mul_f32_e32 v148, v43, v43
	v_pk_fma_f32 v[154:155], v[42:43], v[42:43], v[148:149] op_sel_hi:[1,1,0]
	v_lshlrev_b32_e32 v148, 16, v146
	v_and_b32_e32 v146, 0xffff0000, v146
	v_mul_f32_e32 v146, v37, v146
	v_lshlrev_b32_e32 v37, 16, v147
	v_mul_f32_e32 v38, v38, v37
	v_and_b32_e32 v37, 0xffff0000, v147
	v_lshlrev_b32_e32 v152, 16, v153
	v_and_b32_e32 v153, 0xffff0000, v153
	v_mul_f32_e32 v36, v36, v148
	v_mul_f32_e32 v148, v39, v37
	v_lshlrev_b32_e32 v37, 16, v144
	v_pk_mul_f32 v[46:47], v[46:47], v[152:153]
	v_mul_f32_e32 v151, v32, v37
	v_and_b32_e32 v32, 0xffff0000, v144
	v_mul_f32_e32 v152, v47, v47
	v_mul_f32_e32 v33, v33, v32
	v_mul_f32_e32 v32, v45, v45
	v_pk_fma_f32 v[152:153], v[46:47], v[46:47], v[152:153] op_sel_hi:[1,1,0]
	v_pk_fma_f32 v[160:161], v[44:45], v[44:45], v[32:33] op_sel_hi:[1,1,0]
	v_add_f32_e32 v37, v234, v34
	v_add_f32_e32 v39, v234, v35
	v_mov_b32_e32 v150, v160
	v_mov_b32_e32 v162, v152
	v_mov_b32_e32 v163, v151
	v_pk_add_f32 v[152:153], v[160:161], v[152:153]
	v_pk_mul_f32 v[160:161], v[150:151], v[162:163]
	v_mul_f32_e32 v32, v41, v41
	v_mov_b32_e32 v153, v161
	v_pk_fma_f32 v[160:161], v[40:41], v[40:41], v[32:33] op_sel_hi:[1,1,0]
	v_mov_b32_e32 v162, v154
	v_mov_b32_e32 v32, v160
	v_mov_b32_e32 v163, v33
	v_lshlrev_b32_e32 v157, 16, v145
	v_mov_b32_e32 v156, v36
	v_pk_add_f32 v[154:155], v[160:161], v[154:155]
	v_pk_mul_f32 v[160:161], v[32:33], v[162:163]
	v_and_b32_e32 v159, 0xffff0000, v145
	v_pk_mul_f32 v[34:35], v[36:37], v[156:157]
	v_mov_b32_e32 v147, v37
	v_mov_b32_e32 v156, v146
	v_mov_b32_e32 v158, v38
	v_mov_b32_e32 v155, v161
	v_pk_mul_f32 v[144:145], v[38:39], v[158:159]
	v_mov_b32_e32 v149, v39
	v_mov_b32_e32 v158, v148
	v_pk_add_f32 v[152:153], v[152:153], v[154:155]
	v_pk_fma_f32 v[154:155], v[146:147], v[156:157], v[34:35]
	v_pk_mul_f32 v[156:157], v[34:35], v[34:35]
	v_add_f32_e32 v34, v236, v52
	v_mov_b32_e32 v155, v157
	v_pk_fma_f32 v[156:157], v[148:149], v[158:159], v[144:145]
	v_pk_mul_f32 v[158:159], v[144:145], v[144:145]
	v_and_b32_e32 v161, 0xffff0000, v135
	v_mov_b32_e32 v157, v159
	v_pk_add_f32 v[154:155], v[154:155], v[156:157]
	v_mov_b32_e32 v157, v62
	v_mov_b32_e32 v62, v61
	v_pk_add_f32 v[154:155], v[152:153], v[154:155]
	v_lshlrev_b32_e32 v153, 16, v141
	v_lshlrev_b32_e32 v152, 16, v140
	v_mov_b32_e32 v156, v60
	v_and_b32_e32 v141, 0xffff0000, v141
	v_and_b32_e32 v140, 0xffff0000, v140
	v_pk_add_f32 v[60:61], v[236:237], v[62:63] op_sel_hi:[0,1]
	v_pk_add_f32 v[156:157], v[236:237], v[156:157] op_sel_hi:[0,1]
	v_pk_mul_f32 v[60:61], v[60:61], v[140:141]
	v_pk_mul_f32 v[152:153], v[156:157], v[152:153]
	v_pk_mul_f32 v[62:63], v[60:61], v[60:61]
	v_pk_add_f32 v[154:155], v[154:155], v[154:155] op_sel:[0,1] op_sel_hi:[1,0]
	v_pk_fma_f32 v[62:63], v[152:153], v[152:153], v[62:63]
	v_lshlrev_b32_e32 v159, 16, v135
	v_pk_add_f32 v[140:141], v[62:63], v[62:63] op_sel:[0,1] op_sel_hi:[1,0]
	v_lshlrev_b32_e32 v62, 16, v138
	v_and_b32_e32 v63, 0xffff0000, v138
	v_pk_mul_f32 v[56:57], v[56:57], v[62:63]
	v_lshlrev_b32_e32 v62, 16, v139
	v_and_b32_e32 v63, 0xffff0000, v139
	v_pk_mul_f32 v[58:59], v[58:59], v[62:63]
	v_mov_b32_e32 v162, v140
	v_mul_f32_e32 v32, v59, v59
	v_pk_fma_f32 v[156:157], v[58:59], v[58:59], v[32:33] op_sel_hi:[1,1,0]
	v_lshlrev_b32_e32 v32, 16, v136
	v_mul_f32_e32 v52, v34, v32
	v_and_b32_e32 v32, 0xffff0000, v136
	v_add_f32_e32 v34, v236, v53
	v_mul_f32_e32 v62, v34, v32
	v_lshlrev_b32_e32 v32, 16, v137
	v_add_f32_e32 v34, v236, v54
	v_mul_f32_e32 v136, v34, v32
	v_and_b32_e32 v32, 0xffff0000, v137
	v_add_f32_e32 v34, v236, v55
	v_mul_f32_e32 v138, v34, v32
	v_lshlrev_b32_e32 v32, 16, v134
	v_add_f32_e32 v34, v236, v48
	v_mul_f32_e32 v55, v34, v32
	v_and_b32_e32 v32, 0xffff0000, v134
	v_add_f32_e32 v34, v236, v49
	v_mov_b32_e32 v54, v154
	v_mov_b32_e32 v163, v55
	v_mul_f32_e32 v49, v34, v32
	v_pk_add_f32 v[140:141], v[154:155], v[140:141]
	v_pk_mul_f32 v[154:155], v[54:55], v[162:163]
	v_mul_f32_e32 v32, v57, v57
	v_mov_b32_e32 v141, v155
	v_pk_fma_f32 v[154:155], v[56:57], v[56:57], v[32:33] op_sel_hi:[1,1,0]
	v_mov_b32_e32 v162, v156
	v_mov_b32_e32 v48, v154
	v_mov_b32_e32 v163, v49
	v_add_f32_e32 v53, v236, v50
	v_mov_b32_e32 v158, v52
	v_pk_add_f32 v[154:155], v[154:155], v[156:157]
	v_pk_mul_f32 v[156:157], v[48:49], v[162:163]
	v_add_f32_e32 v137, v236, v51
	v_pk_mul_f32 v[50:51], v[52:53], v[158:159]
	v_mov_b32_e32 v63, v53
	v_mov_b32_e32 v158, v62
	v_mov_b32_e32 v160, v136
	v_mov_b32_e32 v155, v157
	v_pk_mul_f32 v[134:135], v[136:137], v[160:161]
	v_mov_b32_e32 v139, v137
	v_mov_b32_e32 v160, v138
	v_pk_add_f32 v[140:141], v[140:141], v[154:155]
	v_pk_fma_f32 v[154:155], v[62:63], v[158:159], v[50:51]
	v_pk_mul_f32 v[156:157], v[50:51], v[50:51]
	v_pk_mul_f32 v[158:159], v[134:135], v[134:135]
	v_mov_b32_e32 v155, v157
	v_pk_fma_f32 v[156:157], v[138:139], v[160:161], v[134:135]
	v_add_f32_e32 v34, v238, v64
	v_mov_b32_e32 v157, v159
	v_pk_add_f32 v[154:155], v[154:155], v[156:157]
	v_mov_b32_e32 v157, v78
	v_mov_b32_e32 v78, v77
	v_pk_add_f32 v[154:155], v[140:141], v[154:155]
	v_lshlrev_b32_e32 v141, 16, v131
	v_lshlrev_b32_e32 v140, 16, v130
	v_mov_b32_e32 v156, v76
	v_and_b32_e32 v131, 0xffff0000, v131
	v_and_b32_e32 v130, 0xffff0000, v130
	v_pk_add_f32 v[76:77], v[238:239], v[78:79] op_sel_hi:[0,1]
	v_pk_add_f32 v[156:157], v[238:239], v[156:157] op_sel_hi:[0,1]
	v_pk_mul_f32 v[76:77], v[76:77], v[130:131]
	v_pk_mul_f32 v[140:141], v[156:157], v[140:141]
	v_pk_mul_f32 v[78:79], v[76:77], v[76:77]
	v_pk_add_f32 v[154:155], v[154:155], v[154:155] op_sel:[0,1] op_sel_hi:[1,0]
	v_pk_fma_f32 v[78:79], v[140:141], v[140:141], v[78:79]
	v_lshlrev_b32_e32 v159, 16, v125
	v_pk_add_f32 v[130:131], v[78:79], v[78:79] op_sel:[0,1] op_sel_hi:[1,0]
	v_lshlrev_b32_e32 v78, 16, v128
	v_and_b32_e32 v79, 0xffff0000, v128
	v_pk_mul_f32 v[72:73], v[72:73], v[78:79]
	v_lshlrev_b32_e32 v78, 16, v129
	v_and_b32_e32 v79, 0xffff0000, v129
	v_pk_mul_f32 v[74:75], v[74:75], v[78:79]
	v_mov_b32_e32 v162, v130
	v_mul_f32_e32 v32, v75, v75
	v_pk_fma_f32 v[156:157], v[74:75], v[74:75], v[32:33] op_sel_hi:[1,1,0]
	v_lshlrev_b32_e32 v32, 16, v126
	v_mul_f32_e32 v64, v34, v32
	v_and_b32_e32 v32, 0xffff0000, v126
	v_add_f32_e32 v34, v238, v65
	v_mul_f32_e32 v78, v34, v32
	v_lshlrev_b32_e32 v32, 16, v127
	v_add_f32_e32 v34, v238, v66
	v_mul_f32_e32 v126, v34, v32
	v_and_b32_e32 v32, 0xffff0000, v127
	v_add_f32_e32 v34, v238, v67
	v_mul_f32_e32 v128, v34, v32
	v_lshlrev_b32_e32 v32, 16, v124
	v_add_f32_e32 v34, v238, v68
	v_mul_f32_e32 v67, v34, v32
	v_and_b32_e32 v32, 0xffff0000, v124
	v_add_f32_e32 v34, v238, v69
	v_mov_b32_e32 v66, v154
	v_mov_b32_e32 v163, v67
	v_mul_f32_e32 v69, v34, v32
	v_pk_add_f32 v[130:131], v[154:155], v[130:131]
	v_pk_mul_f32 v[154:155], v[66:67], v[162:163]
	v_mul_f32_e32 v32, v73, v73
	v_mov_b32_e32 v131, v155
	v_pk_fma_f32 v[154:155], v[72:73], v[72:73], v[32:33] op_sel_hi:[1,1,0]
	v_mov_b32_e32 v162, v156
	v_mov_b32_e32 v68, v154
	v_mov_b32_e32 v163, v69
	v_add_f32_e32 v65, v238, v70
	v_mov_b32_e32 v158, v64
	v_pk_add_f32 v[154:155], v[154:155], v[156:157]
	v_pk_mul_f32 v[156:157], v[68:69], v[162:163]
	v_and_b32_e32 v161, 0xffff0000, v125
	v_add_f32_e32 v127, v238, v71
	v_pk_mul_f32 v[70:71], v[64:65], v[158:159]
	v_mov_b32_e32 v79, v65
	v_mov_b32_e32 v158, v78
	v_mov_b32_e32 v160, v126
	v_mov_b32_e32 v155, v157
	v_pk_mul_f32 v[124:125], v[126:127], v[160:161]
	v_mov_b32_e32 v129, v127
	v_mov_b32_e32 v160, v128
	v_pk_add_f32 v[130:131], v[130:131], v[154:155]
	v_pk_fma_f32 v[154:155], v[78:79], v[158:159], v[70:71]
	v_pk_mul_f32 v[156:157], v[70:71], v[70:71]
	v_pk_mul_f32 v[158:159], v[124:125], v[124:125]
	v_mov_b32_e32 v155, v157
	v_pk_fma_f32 v[156:157], v[128:129], v[160:161], v[124:125]
	v_add_f32_e32 v34, v240, v84
	v_mov_b32_e32 v157, v159
	v_pk_add_f32 v[154:155], v[154:155], v[156:157]
	v_mov_b32_e32 v157, v94
	v_mov_b32_e32 v94, v93
	v_pk_add_f32 v[154:155], v[130:131], v[154:155]
	v_lshlrev_b32_e32 v131, 16, v121
	v_lshlrev_b32_e32 v130, 16, v120
	v_mov_b32_e32 v156, v92
	v_and_b32_e32 v121, 0xffff0000, v121
	v_and_b32_e32 v120, 0xffff0000, v120
	v_pk_add_f32 v[92:93], v[240:241], v[94:95] op_sel_hi:[0,1]
	v_pk_mul_f32 v[92:93], v[92:93], v[120:121]
	v_lshlrev_b32_e32 v120, 16, v118
	v_and_b32_e32 v121, 0xffff0000, v118
	v_lshlrev_b32_e32 v118, 16, v119
	v_and_b32_e32 v119, 0xffff0000, v119
	v_pk_mul_f32 v[90:91], v[90:91], v[118:119]
	v_pk_add_f32 v[156:157], v[240:241], v[156:157] op_sel_hi:[0,1]
	v_mul_f32_e32 v32, v91, v91
	v_pk_fma_f32 v[118:119], v[90:91], v[90:91], v[32:33] op_sel_hi:[1,1,0]
	v_lshlrev_b32_e32 v32, 16, v116
	v_mul_f32_e32 v84, v34, v32
	v_and_b32_e32 v32, 0xffff0000, v116
	v_add_f32_e32 v34, v240, v85
	v_mul_f32_e32 v116, v34, v32
	v_lshlrev_b32_e32 v32, 16, v117
	v_add_f32_e32 v34, v240, v86
	v_pk_mul_f32 v[130:131], v[156:157], v[130:131]
	v_pk_mul_f32 v[94:95], v[92:93], v[92:93]
	v_mul_f32_e32 v86, v34, v32
	v_and_b32_e32 v32, 0xffff0000, v117
	v_add_f32_e32 v34, v240, v87
	v_pk_fma_f32 v[94:95], v[130:131], v[130:131], v[94:95]
	v_pk_mul_f32 v[88:89], v[88:89], v[120:121]
	v_mul_f32_e32 v120, v34, v32
	v_lshlrev_b32_e32 v32, 16, v114
	v_add_f32_e32 v34, v240, v80
	v_pk_add_f32 v[94:95], v[94:95], v[94:95] op_sel:[0,1] op_sel_hi:[1,0]
	v_mul_f32_e32 v157, v34, v32
	v_pk_add_f32 v[154:155], v[154:155], v[154:155] op_sel:[0,1] op_sel_hi:[1,0]
	v_and_b32_e32 v32, 0xffff0000, v114
	v_add_f32_e32 v34, v240, v81
	v_mov_b32_e32 v156, v154
	v_mov_b32_e32 v162, v94
	v_mov_b32_e32 v163, v157
	v_mul_f32_e32 v81, v34, v32
	v_pk_add_f32 v[94:95], v[154:155], v[94:95]
	v_pk_mul_f32 v[154:155], v[156:157], v[162:163]
	v_mul_f32_e32 v32, v89, v89
	v_mov_b32_e32 v95, v155
	v_pk_fma_f32 v[154:155], v[88:89], v[88:89], v[32:33] op_sel_hi:[1,1,0]
	v_mov_b32_e32 v162, v118
	v_mov_b32_e32 v80, v154
	v_mov_b32_e32 v163, v81
	v_lshlrev_b32_e32 v159, 16, v115
	v_add_f32_e32 v85, v240, v82
	v_mov_b32_e32 v158, v84
	v_pk_add_f32 v[118:119], v[154:155], v[118:119]
	v_pk_mul_f32 v[154:155], v[80:81], v[162:163]
	v_and_b32_e32 v115, 0xffff0000, v115
	v_add_f32_e32 v87, v240, v83
	v_pk_mul_f32 v[82:83], v[84:85], v[158:159]
	v_mov_b32_e32 v117, v85
	v_mov_b32_e32 v158, v116
	v_mov_b32_e32 v114, v86
	v_mov_b32_e32 v119, v155
	v_pk_mul_f32 v[160:161], v[86:87], v[114:115]
	v_mov_b32_e32 v121, v87
	v_mov_b32_e32 v114, v120
	v_pk_add_f32 v[94:95], v[94:95], v[118:119]
	v_pk_fma_f32 v[118:119], v[116:117], v[158:159], v[82:83]
	v_pk_mul_f32 v[154:155], v[82:83], v[82:83]
	v_pk_fma_f32 v[114:115], v[120:121], v[114:115], v[160:161]
	v_mov_b32_e32 v119, v155
	v_pk_mul_f32 v[154:155], v[160:161], v[160:161]
	v_and_b32_e32 v37, 64, v245
	v_mov_b32_e32 v115, v155
	v_xor_b32_e32 v34, 16, v245
	v_add_u32_e32 v37, 64, v37
	v_pk_add_f32 v[114:115], v[118:119], v[114:115]
	v_cmp_lt_i32_e32 vcc, v34, v37
	v_pk_add_f32 v[94:95], v[94:95], v[114:115]
	s_nop 0
	v_cndmask_b32_e32 v34, v245, v34, vcc
	v_add_f32_e32 v32, v94, v95
	v_lshlrev_b32_e32 v34, 2, v34
	ds_bpermute_b32 v34, v34, v32
	v_lshl_add_u64 v[94:95], v[112:113], 0, v[208:209]
	v_lshl_add_u64 v[112:113], v[94:95], 0, s[18:19]
	s_waitcnt lgkmcnt(0)
	v_add_f32_e32 v32, v32, v34
	v_xor_b32_e32 v34, 32, v245
	v_cmp_lt_i32_e32 vcc, v34, v37
	s_nop 1
	v_cndmask_b32_e32 v34, v245, v34, vcc
	v_lshlrev_b32_e32 v34, 2, v34
	ds_bpermute_b32 v34, v34, v32
	s_waitcnt lgkmcnt(0)
	v_add_f32_e32 v32, v32, v34
	v_fmamk_f32 v32, v32, 0x3b800000, v244
	v_cmp_gt_f32_e32 vcc, s7, v32
	v_mul_f32_e32 v34, 0x4b800000, v32
	s_nop 0
	v_cndmask_b32_e32 v32, v32, v34, vcc
	v_rsq_f32_e32 v32, v32
	s_nop 0
	v_mul_f32_e32 v34, 0x45800000, v32
	v_cndmask_b32_e32 v34, v32, v34, vcc
	v_mul_f32_e32 v32, v44, v34
	v_mul_f32_e32 v37, v45, v34
	v_cvt_pk_bf16_f32 v44, v32, v37
	v_mul_f32_e32 v32, v46, v34
	v_add_co_u32_e32 v46, vcc, s47, v94
	v_mul_f32_e32 v37, v47, v34
	v_cvt_pk_bf16_f32 v45, v32, v37
	s_nop 0
	v_addc_co_u32_e32 v47, vcc, 0, v95, vcc
	v_mul_f32_e32 v32, v40, v34
	global_store_dwordx2 v[46:47], v[44:45], off offset:1536
	v_mul_f32_e32 v37, v41, v34
	v_cvt_pk_bf16_f32 v40, v32, v37
	v_mul_f32_e32 v32, v42, v34
	v_mul_f32_e32 v37, v43, v34
	v_cvt_pk_bf16_f32 v41, v32, v37
	v_mul_f32_e32 v32, v36, v34
	v_mul_f32_e32 v36, v146, v34
	global_store_dwordx2 v[112:113], v[40:41], off offset:32
	v_cvt_pk_bf16_f32 v36, v32, v36
	v_mul_f32_e32 v32, v38, v34
	v_mul_f32_e32 v37, v148, v34
	v_cvt_pk_bf16_f32 v37, v32, v37
	v_mul_f32_e32 v32, v151, v34
	v_mul_f32_e32 v33, v33, v34
	global_store_dwordx2 v[112:113], v[36:37], off offset:64
	v_cvt_pk_bf16_f32 v32, v32, v33
	v_mul_f32_e32 v33, v35, v34
	v_mul_f32_e32 v35, v145, v34
	v_cvt_pk_bf16_f32 v33, v33, v35
	global_store_dwordx2 v[112:113], v[32:33], off offset:96
	v_mul_f32_e32 v32, v152, v34
	v_mul_f32_e32 v33, v60, v34
	v_cvt_pk_bf16_f32 v32, v32, v33
	v_mul_f32_e32 v33, v153, v34
	v_mul_f32_e32 v35, v61, v34
	v_cvt_pk_bf16_f32 v33, v33, v35
	global_store_dwordx2 v[112:113], v[32:33], off offset:128
	v_mul_f32_e32 v32, v56, v34
	v_mul_f32_e32 v33, v57, v34
	v_cvt_pk_bf16_f32 v32, v32, v33
	v_mul_f32_e32 v33, v58, v34
	v_mul_f32_e32 v35, v59, v34
	v_cvt_pk_bf16_f32 v33, v33, v35
	global_store_dwordx2 v[112:113], v[32:33], off offset:160
	v_mul_f32_e32 v32, v52, v34
	v_mul_f32_e32 v33, v62, v34
	v_cvt_pk_bf16_f32 v32, v32, v33
	v_mul_f32_e32 v33, v136, v34
	v_mul_f32_e32 v35, v138, v34
	v_cvt_pk_bf16_f32 v33, v33, v35
	global_store_dwordx2 v[112:113], v[32:33], off offset:192
	v_mul_f32_e32 v32, v55, v34
	v_mul_f32_e32 v33, v49, v34
	v_cvt_pk_bf16_f32 v32, v32, v33
	v_mul_f32_e32 v33, v51, v34
	v_mul_f32_e32 v35, v135, v34
	v_cvt_pk_bf16_f32 v33, v33, v35
	global_store_dwordx2 v[112:113], v[32:33], off offset:224
	v_mul_f32_e32 v32, v140, v34
	v_mul_f32_e32 v33, v76, v34
	v_cvt_pk_bf16_f32 v32, v32, v33
	v_mul_f32_e32 v33, v141, v34
	v_mul_f32_e32 v35, v77, v34
	v_cvt_pk_bf16_f32 v33, v33, v35
	global_store_dwordx2 v[112:113], v[32:33], off offset:256
	v_mul_f32_e32 v32, v72, v34
	v_mul_f32_e32 v33, v73, v34
	v_cvt_pk_bf16_f32 v32, v32, v33
	v_mul_f32_e32 v33, v74, v34
	v_mul_f32_e32 v35, v75, v34
	v_cvt_pk_bf16_f32 v33, v33, v35
	global_store_dwordx2 v[112:113], v[32:33], off offset:288
	v_mul_f32_e32 v32, v64, v34
	v_mul_f32_e32 v33, v78, v34
	v_cvt_pk_bf16_f32 v32, v32, v33
	v_mul_f32_e32 v33, v126, v34
	v_mul_f32_e32 v35, v128, v34
	v_cvt_pk_bf16_f32 v33, v33, v35
	global_store_dwordx2 v[112:113], v[32:33], off offset:320
	v_mul_f32_e32 v32, v67, v34
	v_mul_f32_e32 v33, v69, v34
	v_cvt_pk_bf16_f32 v32, v32, v33
	v_mul_f32_e32 v33, v71, v34
	v_mul_f32_e32 v35, v125, v34
	v_cvt_pk_bf16_f32 v33, v33, v35
	global_store_dwordx2 v[112:113], v[32:33], off offset:352
	v_mul_f32_e32 v32, v130, v34
	v_mul_f32_e32 v33, v92, v34
	v_cvt_pk_bf16_f32 v32, v32, v33
	v_mul_f32_e32 v33, v131, v34
	v_mul_f32_e32 v35, v93, v34
	v_cvt_pk_bf16_f32 v33, v33, v35
	global_store_dwordx2 v[112:113], v[32:33], off offset:384
	v_mul_f32_e32 v32, v88, v34
	v_mul_f32_e32 v33, v89, v34
	v_cvt_pk_bf16_f32 v32, v32, v33
	v_mul_f32_e32 v33, v90, v34
	v_mul_f32_e32 v35, v91, v34
	v_cvt_pk_bf16_f32 v33, v33, v35
	global_store_dwordx2 v[112:113], v[32:33], off offset:416
	v_mul_f32_e32 v32, v84, v34
	v_mul_f32_e32 v33, v116, v34
	v_cvt_pk_bf16_f32 v32, v32, v33
	v_mul_f32_e32 v33, v86, v34
	v_mul_f32_e32 v35, v120, v34
	v_cvt_pk_bf16_f32 v33, v33, v35
	global_store_dwordx2 v[112:113], v[32:33], off offset:448
	v_mul_f32_e32 v32, v157, v34
	v_mul_f32_e32 v33, v81, v34
	v_cvt_pk_bf16_f32 v32, v32, v33
	v_mul_f32_e32 v33, v83, v34
	v_mul_f32_e32 v34, v161, v34
	v_cvt_pk_bf16_f32 v33, v33, v34
	global_store_dwordx2 v[112:113], v[32:33], off offset:480
	s_barrier
	s_cbranch_scc0 .LBB0_242
